# G3 output epilogue: sixteen r-chunk loads and four gain loads issued together, one wait, stores not waited for (epilogue de-serialisation)
# speedup vs baseline: 1.0024x; 1.0024x over previous
; __device__ __forceinline__ float bf_lo(unsigned u) { return __uint_as_float(u << 16); }
; __device__ __forceinline__ float bf_hi(unsigned u) { return __uint_as_float(u & 0xffff0000u); }
; __device__ __forceinline__ float siluf_(float x) { return x * __builtin_amdgcn_rcpf(1.f + __expf(-x)); }
; __device__ void phaseG3_task(const Params& p, int task, char* lds, bf16_t* ydst, int ystride) {
;     ...
; #pragma unroll
;     for (int tt = 0; tt < 4; tt++) {
;         const int t = tt * 16 + r;
;         const float tot = red[t] + red[64 + t] + red[128 + t] + red[192 + t];
;         const float rstd = rsqrtf(tot * (1.f / 256.f) + 1e-6f);
; #pragma unroll
;         for (int et = 0; et < 4; et++) {
;             const int e = (wave * 4 + et) * 16 + 4 * q;
;             bf16_t* rp = Z + (size_t)(tok0 + t) * ZC + ZR_G + h * 256 + e;
;             const u32x2 rv = *(const u32x2*)rp;
;             const f32x4 gn = *(const f32x4*)(p.gla_norm_g + e);
;             const float r0 = bf_lo(rv.x), r1 = bf_hi(rv.x), r2 = bf_lo(rv.y), r3 = bf_hi(rv.y);
;             const f32x4 ov = o[et][tt];
;             *(u32x2*)(ydst + (size_t)(tok0 + t) * ystride + h * 256 + e) = (u32x2){pack2(ov[0] * rstd * gn[0] * siluf_(r0), ov[1] * rstd * gn[1] * siluf_(r1)),
;                                   pack2(ov[2] * rstd * gn[2] * siluf_(r2), ov[3] * rstd * gn[3] * siluf_(r3))};
;         }
;     }
.LBB0_634:
	s_or_b64 exec, exec, s[4:5]
	v_or_b32_e32 v69, v67, v66
	v_or_b32_e32 v96, s0, v68
	v_mov_b64_e32 v[66:67], s[6:7]
	s_lshl_b32 s10, s10, 1
	v_mad_i64_i32 v[70:71], s[4:5], v96, s41, v[66:67]
	v_lshl_add_u64 v[70:71], v[70:71], 0, s[10:11]
	v_lshlrev_b32_e32 v64, 1, v69
	v_lshl_add_u64 v[72:73], v[70:71], 0, v[64:65]
	v_add_co_u32_e32 v70, vcc, s9, v72
	s_waitcnt lgkmcnt(0)
	s_nop 0
	v_addc_co_u32_e32 v71, vcc, 0, v73, vcc
	s_barrier
	s_load_dwordx2 s[4:5], s[30:31], 0x58
	v_lshlrev_b32_e32 v79, 2, v69
	v_lshl_add_u32 v68, v68, 2, s2
	v_lshl_add_u32 v69, v81, 2, s2
	v_lshl_add_u64 v[94:95], v[72:73], 0, s[22:23]
	s_waitcnt lgkmcnt(0)
	s_lshl_b32 s46, s41, 4
	s_mov_b32 s47, 0
	v_mov_b32_e32 v146, v70
	v_mov_b32_e32 v147, v71
	v_lshl_add_u64 v[148:149], v[146:147], 0, s[46:47]
	v_lshl_add_u64 v[150:151], v[148:149], 0, s[46:47]
	v_lshl_add_u64 v[152:153], v[150:151], 0, s[46:47]
	global_load_dwordx2 v[98:99], v[146:147], off
	global_load_dwordx2 v[100:101], v[146:147], off offset:32
	global_load_dwordx2 v[102:103], v[146:147], off offset:64
	global_load_dwordx2 v[104:105], v[146:147], off offset:96
	global_load_dwordx2 v[106:107], v[148:149], off
	global_load_dwordx2 v[108:109], v[148:149], off offset:32
	global_load_dwordx2 v[110:111], v[148:149], off offset:64
	global_load_dwordx2 v[112:113], v[148:149], off offset:96
	global_load_dwordx2 v[114:115], v[150:151], off
	global_load_dwordx2 v[116:117], v[150:151], off offset:32
	global_load_dwordx2 v[118:119], v[150:151], off offset:64
	global_load_dwordx2 v[120:121], v[150:151], off offset:96
	global_load_dwordx2 v[122:123], v[152:153], off
	global_load_dwordx2 v[124:125], v[152:153], off offset:32
	global_load_dwordx2 v[126:127], v[152:153], off offset:64
	global_load_dwordx2 v[128:129], v[152:153], off offset:96
	global_load_dwordx4 v[130:133], v79, s[4:5]
	global_load_dwordx4 v[134:137], v79, s[4:5] offset:64
	global_load_dwordx4 v[138:141], v79, s[4:5] offset:128
	global_load_dwordx4 v[142:145], v79, s[4:5] offset:192
	ds_read2st64_b32 v[74:75], v68 offset1:1
	ds_read2st64_b32 v[88:89], v68 offset0:2 offset1:3
	ds_read2st64_b32 v[90:91], v69 offset1:1
	ds_read2st64_b32 v[92:93], v69 offset0:2 offset1:3
	v_mov_b64_e32 v[70:71], s[26:27]
	s_waitcnt lgkmcnt(3)
	v_mov_b32_e32 v73, v74
	s_add_u32 s6, s28, s10
	s_waitcnt lgkmcnt(1)
	v_mov_b32_e32 v72, v90
	v_mov_b32_e32 v74, v91
	s_waitcnt lgkmcnt(0)
	v_mov_b32_e32 v90, v92
	v_mov_b32_e32 v91, v88
	v_pk_add_f32 v[72:73], v[72:73], v[74:75]
	v_mov_b32_e32 v88, v93
	v_pk_add_f32 v[72:73], v[72:73], v[90:91]
	s_addc_u32 s7, s29, 0
	v_pk_add_f32 v[72:73], v[72:73], v[88:89]
	s_add_u32 s6, s6, 0x5c01000
	v_pk_fma_f32 v[72:73], v[72:73], s[24:25], v[70:71] op_sel_hi:[1,0,0]
	s_addc_u32 s7, s7, 0
	v_mul_f32_e32 v74, 0x4b800000, v73
	v_cmp_gt_f32_e32 vcc, s44, v73
	v_mov_b64_e32 v[68:69], s[6:7]
	s_add_i32 s1, s1, s8
	v_cndmask_b32_e32 v73, v73, v74, vcc
	v_rsq_f32_e32 v73, v73
	v_mad_i64_i32 v[74:75], s[6:7], v96, s41, v[68:69]
	v_lshl_add_u64 v[74:75], v[74:75], 0, v[64:65]
	v_mul_f32_e32 v88, 0x45800000, v73
	v_cndmask_b32_e32 v88, v73, v88, vcc
	v_pk_mul_f32 v[60:61], v[60:61], v[88:89] op_sel_hi:[1,0]
	v_pk_mul_f32 v[62:63], v[62:63], v[88:89] op_sel_hi:[1,0]
	s_add_i32 s3, s3, s21
	s_waitcnt vmcnt(0)
	v_lshlrev_b32_e32 v90, 16, v98
	v_and_b32_e32 v91, 0xffff0000, v98
	v_lshlrev_b32_e32 v98, 16, v99
	v_and_b32_e32 v99, 0xffff0000, v99
	v_mul_f32_e32 v73, 0xbfb8aa3b, v90
	v_mul_f32_e32 v89, 0xbfb8aa3b, v91
	v_mul_f32_e32 v92, 0xbfb8aa3b, v98
	v_mul_f32_e32 v93, 0xbfb8aa3b, v99
	v_exp_f32_e32 v73, v73
	v_exp_f32_e32 v89, v89
	v_exp_f32_e32 v92, v92
	v_exp_f32_e32 v93, v93
	v_add_f32_e32 v73, 1.0, v73
	v_add_f32_e32 v89, 1.0, v89
	v_add_f32_e32 v96, 1.0, v92
	v_add_f32_e32 v97, 1.0, v93
	v_rcp_f32_e32 v92, v73
	v_rcp_f32_e32 v93, v89
	v_rcp_f32_e32 v96, v96
	v_rcp_f32_e32 v97, v97
	v_pk_mul_f32 v[60:61], v[130:131], v[60:61]
	v_pk_mul_f32 v[62:63], v[132:133], v[62:63]
	v_pk_mul_f32 v[82:83], v[92:93], v[90:91]
	v_pk_mul_f32 v[84:85], v[96:97], v[98:99]
	v_pk_mul_f32 v[60:61], v[82:83], v[60:61]
	v_pk_mul_f32 v[62:63], v[84:85], v[62:63]
	v_cvt_pk_bf16_f32 v60, v60, v61
	v_cvt_pk_bf16_f32 v61, v62, v63
	global_store_dwordx2 v[74:75], v[60:61], off
	s_nop 0
	v_pk_mul_f32 v[56:57], v[56:57], v[88:89] op_sel_hi:[1,0]
	v_pk_mul_f32 v[58:59], v[58:59], v[88:89] op_sel_hi:[1,0]
	v_lshlrev_b32_e32 v84, 16, v100
	v_and_b32_e32 v85, 0xffff0000, v100
	v_lshlrev_b32_e32 v100, 16, v101
	v_and_b32_e32 v101, 0xffff0000, v101
	v_mul_f32_e32 v73, 0xbfb8aa3b, v84
	v_mul_f32_e32 v86, 0xbfb8aa3b, v85
	v_mul_f32_e32 v87, 0xbfb8aa3b, v100
	v_mul_f32_e32 v89, 0xbfb8aa3b, v101
	v_exp_f32_e32 v73, v73
	v_exp_f32_e32 v86, v86
	v_exp_f32_e32 v87, v87
	v_exp_f32_e32 v89, v89
	v_add_f32_e32 v73, 1.0, v73
	v_add_f32_e32 v90, 1.0, v86
	v_add_f32_e32 v91, 1.0, v87
	v_add_f32_e32 v89, 1.0, v89
	v_rcp_f32_e32 v86, v73
	v_rcp_f32_e32 v87, v90
	v_rcp_f32_e32 v90, v91
	v_rcp_f32_e32 v91, v89
	v_pk_mul_f32 v[56:57], v[134:135], v[56:57]
	v_pk_mul_f32 v[58:59], v[136:137], v[58:59]
	v_pk_mul_f32 v[60:61], v[86:87], v[84:85]
	v_pk_mul_f32 v[62:63], v[90:91], v[100:101]
	v_pk_mul_f32 v[56:57], v[56:57], v[60:61]
	v_pk_mul_f32 v[58:59], v[58:59], v[62:63]
	v_cvt_pk_bf16_f32 v56, v56, v57
	v_cvt_pk_bf16_f32 v57, v58, v59
	global_store_dwordx2 v[74:75], v[56:57], off offset:32
	s_nop 0
	v_pk_mul_f32 v[52:53], v[52:53], v[88:89] op_sel_hi:[1,0]
	v_pk_mul_f32 v[54:55], v[54:55], v[88:89] op_sel_hi:[1,0]
	v_pk_mul_f32 v[48:49], v[48:49], v[88:89] op_sel_hi:[1,0]
	v_pk_mul_f32 v[50:51], v[50:51], v[88:89] op_sel_hi:[1,0]
	v_lshlrev_b32_e32 v62, 16, v102
	v_and_b32_e32 v63, 0xffff0000, v102
; __device__ __forceinline__ float bf_lo(unsigned u) { return __uint_as_float(u << 16); }
; __device__ __forceinline__ float bf_hi(unsigned u) { return __uint_as_float(u & 0xffff0000u); }
; __device__ __forceinline__ float siluf_(float x) { return x * __builtin_amdgcn_rcpf(1.f + __expf(-x)); }
; __device__ void phaseG3_task(const Params& p, int task, char* lds, bf16_t* ydst, int ystride) {
;     ...
; #pragma unroll
;     for (int tt = 0; tt < 4; tt++) {
;         const int t = tt * 16 + r;
;         const float tot = red[t] + red[64 + t] + red[128 + t] + red[192 + t];
;         const float rstd = rsqrtf(tot * (1.f / 256.f) + 1e-6f);
; #pragma unroll
;         for (int et = 0; et < 4; et++) {
;             const int e = (wave * 4 + et) * 16 + 4 * q;
;             bf16_t* rp = Z + (size_t)(tok0 + t) * ZC + ZR_G + h * 256 + e;
;             const u32x2 rv = *(const u32x2*)rp;
;             const f32x4 gn = *(const f32x4*)(p.gla_norm_g + e);
;             const float r0 = bf_lo(rv.x), r1 = bf_hi(rv.x), r2 = bf_lo(rv.y), r3 = bf_hi(rv.y);
;             const f32x4 ov = o[et][tt];
;             *(u32x2*)(ydst + (size_t)(tok0 + t) * ystride + h * 256 + e) = (u32x2){pack2(ov[0] * rstd * gn[0] * siluf_(r0), ov[1] * rstd * gn[1] * siluf_(r1)),
;                                   pack2(ov[2] * rstd * gn[2] * siluf_(r2), ov[3] * rstd * gn[3] * siluf_(r3))};
;         }
;     }
	v_lshlrev_b32_e32 v102, 16, v103
	v_and_b32_e32 v103, 0xffff0000, v103
	v_mul_f32_e32 v73, 0xbfb8aa3b, v62
	v_mul_f32_e32 v82, 0xbfb8aa3b, v63
	v_mul_f32_e32 v83, 0xbfb8aa3b, v102
	v_mul_f32_e32 v84, 0xbfb8aa3b, v103
	v_exp_f32_e32 v73, v73
	v_exp_f32_e32 v82, v82
	v_exp_f32_e32 v83, v83
	v_exp_f32_e32 v84, v84
	v_add_f32_e32 v73, 1.0, v73
	v_add_f32_e32 v85, 1.0, v82
	v_add_f32_e32 v86, 1.0, v83
	v_add_f32_e32 v87, 1.0, v84
	v_rcp_f32_e32 v82, v73
	v_rcp_f32_e32 v83, v85
	v_rcp_f32_e32 v84, v86
	v_rcp_f32_e32 v85, v87
	v_pk_mul_f32 v[52:53], v[52:53], v[138:139]
	v_pk_mul_f32 v[54:55], v[54:55], v[140:141]
	v_pk_mul_f32 v[56:57], v[82:83], v[62:63]
	v_pk_mul_f32 v[58:59], v[84:85], v[102:103]
	v_pk_mul_f32 v[52:53], v[52:53], v[56:57]
	v_pk_mul_f32 v[54:55], v[54:55], v[58:59]
	v_cvt_pk_bf16_f32 v52, v52, v53
	v_cvt_pk_bf16_f32 v53, v54, v55
	global_store_dwordx2 v[74:75], v[52:53], off offset:64
	s_nop 0
	v_or_b32_e32 v73, s0, v81
	v_mad_i64_i32 v[58:59], s[6:7], v73, s41, v[66:67]
	v_lshl_add_u64 v[58:59], v[58:59], 0, s[10:11]
	v_lshl_add_u64 v[58:59], v[58:59], 0, v[64:65]
	v_add_co_u32_e32 v60, vcc, s9, v58
	v_lshlrev_b32_e32 v62, 16, v104
	v_and_b32_e32 v63, 0xffff0000, v104
	v_lshlrev_b32_e32 v104, 16, v105
	v_and_b32_e32 v105, 0xffff0000, v105
	v_mul_f32_e32 v81, 0xbfb8aa3b, v62
	v_mul_f32_e32 v82, 0xbfb8aa3b, v63
	v_mul_f32_e32 v83, 0xbfb8aa3b, v104
	v_mul_f32_e32 v84, 0xbfb8aa3b, v105
	v_exp_f32_e32 v81, v81
	v_exp_f32_e32 v82, v82
	v_exp_f32_e32 v83, v83
	v_exp_f32_e32 v84, v84
	v_add_f32_e32 v81, 1.0, v81
	v_add_f32_e32 v85, 1.0, v82
	v_add_f32_e32 v86, 1.0, v83
	v_add_f32_e32 v87, 1.0, v84
	v_rcp_f32_e32 v82, v81
	v_rcp_f32_e32 v83, v85
	v_rcp_f32_e32 v84, v86
	v_rcp_f32_e32 v85, v87
	v_pk_mul_f32 v[48:49], v[48:49], v[142:143]
	v_pk_mul_f32 v[50:51], v[50:51], v[144:145]
	v_pk_mul_f32 v[52:53], v[82:83], v[62:63]
	v_pk_mul_f32 v[54:55], v[84:85], v[104:105]
	v_pk_mul_f32 v[48:49], v[48:49], v[52:53]
	v_pk_mul_f32 v[50:51], v[50:51], v[54:55]
	v_cvt_pk_bf16_f32 v48, v48, v49
	v_cvt_pk_bf16_f32 v49, v50, v51
	v_addc_co_u32_e32 v61, vcc, 0, v59, vcc
	global_store_dwordx2 v[74:75], v[48:49], off offset:96
	v_mul_f32_e32 v48, 0x4b800000, v72
	v_cmp_gt_f32_e32 vcc, s44, v72
	v_lshl_add_u64 v[56:57], v[58:59], 0, s[22:23]
	v_lshlrev_b32_e32 v60, 16, v106
	v_cndmask_b32_e32 v48, v72, v48, vcc
	v_rsq_f32_e32 v58, v48
	v_and_b32_e32 v61, 0xffff0000, v106
	v_lshlrev_b32_e32 v106, 16, v107
	v_and_b32_e32 v107, 0xffff0000, v107
	v_mul_f32_e32 v59, 0x45800000, v58
	v_cndmask_b32_e32 v58, v58, v59, vcc
	v_pk_mul_f32 v[44:45], v[44:45], v[58:59] op_sel_hi:[1,0]
	v_pk_mul_f32 v[46:47], v[46:47], v[58:59] op_sel_hi:[1,0]
	v_mul_f32_e32 v59, 0xbfb8aa3b, v60
	v_mul_f32_e32 v62, 0xbfb8aa3b, v61
	v_mul_f32_e32 v63, 0xbfb8aa3b, v106
	v_mul_f32_e32 v72, 0xbfb8aa3b, v107
	v_exp_f32_e32 v59, v59
	v_exp_f32_e32 v62, v62
	v_exp_f32_e32 v63, v63
	v_exp_f32_e32 v72, v72
	v_mad_i64_i32 v[48:49], s[6:7], v73, s41, v[68:69]
	v_add_f32_e32 v59, 1.0, v59
	v_add_f32_e32 v73, 1.0, v62
	v_add_f32_e32 v74, 1.0, v63
	v_add_f32_e32 v75, 1.0, v72
	v_rcp_f32_e32 v62, v59
	v_rcp_f32_e32 v63, v73
	v_rcp_f32_e32 v72, v74
	v_rcp_f32_e32 v73, v75
	v_pk_mul_f32 v[44:45], v[130:131], v[44:45]
	v_pk_mul_f32 v[46:47], v[132:133], v[46:47]
	v_pk_mul_f32 v[50:51], v[62:63], v[60:61]
	v_pk_mul_f32 v[52:53], v[72:73], v[106:107]
	v_pk_mul_f32 v[44:45], v[50:51], v[44:45]
	v_pk_mul_f32 v[46:47], v[52:53], v[46:47]
	v_lshl_add_u64 v[48:49], v[48:49], 0, v[64:65]
	v_cvt_pk_bf16_f32 v44, v44, v45
	v_cvt_pk_bf16_f32 v45, v46, v47
	global_store_dwordx2 v[48:49], v[44:45], off
	s_nop 0
	v_pk_mul_f32 v[40:41], v[40:41], v[58:59] op_sel_hi:[1,0]
	v_pk_mul_f32 v[42:43], v[42:43], v[58:59] op_sel_hi:[1,0]
	v_lshlrev_b32_e32 v52, 16, v108
	v_and_b32_e32 v53, 0xffff0000, v108
	v_lshlrev_b32_e32 v108, 16, v109
	v_and_b32_e32 v109, 0xffff0000, v109
	v_mul_f32_e32 v54, 0xbfb8aa3b, v52
	v_mul_f32_e32 v55, 0xbfb8aa3b, v53
	v_mul_f32_e32 v59, 0xbfb8aa3b, v108
	v_mul_f32_e32 v60, 0xbfb8aa3b, v109
	v_exp_f32_e32 v54, v54
	v_exp_f32_e32 v55, v55
	v_exp_f32_e32 v59, v59
	v_exp_f32_e32 v60, v60
	v_add_f32_e32 v54, 1.0, v54
	v_add_f32_e32 v55, 1.0, v55
	v_add_f32_e32 v59, 1.0, v59
	v_add_f32_e32 v61, 1.0, v60
	v_rcp_f32_e32 v54, v54
	v_rcp_f32_e32 v55, v55
	v_rcp_f32_e32 v60, v59
	v_rcp_f32_e32 v61, v61
	v_pk_mul_f32 v[40:41], v[134:135], v[40:41]
	v_pk_mul_f32 v[42:43], v[136:137], v[42:43]
	v_pk_mul_f32 v[44:45], v[54:55], v[52:53]
	v_pk_mul_f32 v[46:47], v[60:61], v[108:109]
	v_pk_mul_f32 v[40:41], v[40:41], v[44:45]
	v_pk_mul_f32 v[42:43], v[42:43], v[46:47]
	v_cvt_pk_bf16_f32 v40, v40, v41
	v_cvt_pk_bf16_f32 v41, v42, v43
	global_store_dwordx2 v[48:49], v[40:41], off offset:32
	s_nop 0
	v_pk_mul_f32 v[36:37], v[36:37], v[58:59] op_sel_hi:[1,0]
	v_pk_mul_f32 v[38:39], v[38:39], v[58:59] op_sel_hi:[1,0]
	v_or_b32_e32 v54, s0, v80
	v_pk_mul_f32 v[32:33], v[32:33], v[58:59] op_sel_hi:[1,0]
	v_pk_mul_f32 v[34:35], v[34:35], v[58:59] op_sel_hi:[1,0]
	v_lshlrev_b32_e32 v46, 16, v110
	v_and_b32_e32 v47, 0xffff0000, v110
	v_lshlrev_b32_e32 v110, 16, v111
	v_and_b32_e32 v111, 0xffff0000, v111
	v_mul_f32_e32 v50, 0xbfb8aa3b, v46
	v_mul_f32_e32 v51, 0xbfb8aa3b, v47
	v_mul_f32_e32 v52, 0xbfb8aa3b, v110
	v_mul_f32_e32 v53, 0xbfb8aa3b, v111
	v_exp_f32_e32 v50, v50
	v_exp_f32_e32 v51, v51
	v_exp_f32_e32 v52, v52
	v_exp_f32_e32 v53, v53
	v_add_f32_e32 v50, 1.0, v50
	v_add_f32_e32 v51, 1.0, v51
	v_add_f32_e32 v52, 1.0, v52
	v_add_f32_e32 v53, 1.0, v53
	v_rcp_f32_e32 v50, v50
	v_rcp_f32_e32 v51, v51
	v_rcp_f32_e32 v52, v52
	v_rcp_f32_e32 v53, v53
	v_pk_mul_f32 v[36:37], v[138:139], v[36:37]
; __device__ __forceinline__ float bf_lo(unsigned u) { return __uint_as_float(u << 16); }
; __device__ __forceinline__ float bf_hi(unsigned u) { return __uint_as_float(u & 0xffff0000u); }
; __device__ __forceinline__ float siluf_(float x) { return x * __builtin_amdgcn_rcpf(1.f + __expf(-x)); }
; __device__ void phaseG3_task(const Params& p, int task, char* lds, bf16_t* ydst, int ystride) {
;     ...
; #pragma unroll
;     for (int tt = 0; tt < 4; tt++) {
;         const int t = tt * 16 + r;
;         const float tot = red[t] + red[64 + t] + red[128 + t] + red[192 + t];
;         const float rstd = rsqrtf(tot * (1.f / 256.f) + 1e-6f);
; #pragma unroll
;         for (int et = 0; et < 4; et++) {
;             const int e = (wave * 4 + et) * 16 + 4 * q;
;             bf16_t* rp = Z + (size_t)(tok0 + t) * ZC + ZR_G + h * 256 + e;
;             const u32x2 rv = *(const u32x2*)rp;
;             const f32x4 gn = *(const f32x4*)(p.gla_norm_g + e);
;             const float r0 = bf_lo(rv.x), r1 = bf_hi(rv.x), r2 = bf_lo(rv.y), r3 = bf_hi(rv.y);
;             const f32x4 ov = o[et][tt];
;             *(u32x2*)(ydst + (size_t)(tok0 + t) * ystride + h * 256 + e) = (u32x2){pack2(ov[0] * rstd * gn[0] * siluf_(r0), ov[1] * rstd * gn[1] * siluf_(r1)),
;                                   pack2(ov[2] * rstd * gn[2] * siluf_(r2), ov[3] * rstd * gn[3] * siluf_(r3))};
;         }
;     }
	v_pk_mul_f32 v[38:39], v[140:141], v[38:39]
	v_pk_mul_f32 v[40:41], v[50:51], v[46:47]
	v_pk_mul_f32 v[42:43], v[52:53], v[110:111]
	v_pk_mul_f32 v[36:37], v[36:37], v[40:41]
	v_pk_mul_f32 v[38:39], v[38:39], v[42:43]
	v_cvt_pk_bf16_f32 v36, v36, v37
	v_cvt_pk_bf16_f32 v37, v38, v39
	global_store_dwordx2 v[48:49], v[36:37], off offset:64
	s_nop 0
	v_mad_i64_i32 v[42:43], s[6:7], v54, s41, v[66:67]
	v_lshl_add_u64 v[42:43], v[42:43], 0, s[10:11]
	v_lshl_add_u64 v[42:43], v[42:43], 0, v[64:65]
	v_add_co_u32_e32 v44, vcc, s9, v42
	v_lshlrev_b32_e32 v46, 16, v112
	v_and_b32_e32 v47, 0xffff0000, v112
	v_lshlrev_b32_e32 v112, 16, v113
	v_and_b32_e32 v113, 0xffff0000, v113
	v_mul_f32_e32 v50, 0xbfb8aa3b, v46
	v_mul_f32_e32 v51, 0xbfb8aa3b, v47
	v_mul_f32_e32 v52, 0xbfb8aa3b, v112
	v_mul_f32_e32 v53, 0xbfb8aa3b, v113
	v_exp_f32_e32 v50, v50
	v_exp_f32_e32 v51, v51
	v_exp_f32_e32 v52, v52
	v_exp_f32_e32 v53, v53
	v_add_f32_e32 v50, 1.0, v50
	v_add_f32_e32 v51, 1.0, v51
	v_add_f32_e32 v52, 1.0, v52
	v_add_f32_e32 v53, 1.0, v53
	v_rcp_f32_e32 v50, v50
	v_rcp_f32_e32 v51, v51
	v_rcp_f32_e32 v52, v52
	v_rcp_f32_e32 v53, v53
	v_pk_mul_f32 v[32:33], v[32:33], v[142:143]
	v_pk_mul_f32 v[34:35], v[34:35], v[144:145]
	v_pk_mul_f32 v[36:37], v[50:51], v[46:47]
	v_pk_mul_f32 v[38:39], v[52:53], v[112:113]
	v_pk_mul_f32 v[32:33], v[32:33], v[36:37]
	v_pk_mul_f32 v[34:35], v[34:35], v[38:39]
	v_cvt_pk_bf16_f32 v32, v32, v33
	v_cvt_pk_bf16_f32 v33, v34, v35
	v_addc_co_u32_e32 v45, vcc, 0, v43, vcc
	global_store_dwordx2 v[48:49], v[32:33], off offset:96
	v_lshl_add_u32 v44, v80, 2, s2
	v_lshl_add_u32 v46, v78, 2, s2
	ds_read2st64_b32 v[32:33], v46 offset1:1
	ds_read2st64_b32 v[34:35], v44 offset1:1
	ds_read2st64_b32 v[44:45], v44 offset0:2 offset1:3
	ds_read2st64_b32 v[46:47], v46 offset0:2 offset1:3
	v_lshl_add_u64 v[42:43], v[42:43], 0, s[22:23]
	s_waitcnt lgkmcnt(3)
	v_mov_b32_e32 v48, v32
	s_waitcnt lgkmcnt(2)
	v_mov_b32_e32 v49, v34
	v_mov_b32_e32 v34, v33
	s_waitcnt lgkmcnt(0)
	v_mov_b32_e32 v32, v46
	v_mov_b32_e32 v33, v44
	v_pk_add_f32 v[34:35], v[48:49], v[34:35]
	v_mov_b32_e32 v44, v47
	v_pk_add_f32 v[32:33], v[34:35], v[32:33]
	v_lshlrev_b32_e32 v46, 16, v114
	v_pk_add_f32 v[32:33], v[32:33], v[44:45]
	v_and_b32_e32 v47, 0xffff0000, v114
	v_pk_fma_f32 v[32:33], v[32:33], s[24:25], v[70:71] op_sel_hi:[1,0,0]
	v_lshlrev_b32_e32 v114, 16, v115
	v_mul_f32_e32 v34, 0x4b800000, v33
	v_cmp_gt_f32_e32 vcc, s44, v33
	v_and_b32_e32 v115, 0xffff0000, v115
	v_mul_f32_e32 v48, 0xbfb8aa3b, v114
	v_cndmask_b32_e32 v33, v33, v34, vcc
	v_rsq_f32_e32 v33, v33
	v_mul_f32_e32 v49, 0xbfb8aa3b, v115
	v_exp_f32_e32 v48, v48
	v_exp_f32_e32 v49, v49
	v_mul_f32_e32 v44, 0x45800000, v33
	v_cndmask_b32_e32 v44, v33, v44, vcc
	v_pk_mul_f32 v[28:29], v[28:29], v[44:45] op_sel_hi:[1,0]
	v_pk_mul_f32 v[30:31], v[30:31], v[44:45] op_sel_hi:[1,0]
	v_mul_f32_e32 v33, 0xbfb8aa3b, v46
	v_mul_f32_e32 v45, 0xbfb8aa3b, v47
	v_exp_f32_e32 v33, v33
	v_exp_f32_e32 v45, v45
	v_add_f32_e32 v50, 1.0, v48
	v_add_f32_e32 v51, 1.0, v49
	v_add_f32_e32 v33, 1.0, v33
	v_add_f32_e32 v45, 1.0, v45
	v_rcp_f32_e32 v48, v33
	v_rcp_f32_e32 v49, v45
	v_rcp_f32_e32 v50, v50
	v_rcp_f32_e32 v51, v51
	v_pk_mul_f32 v[28:29], v[130:131], v[28:29]
	v_pk_mul_f32 v[30:31], v[132:133], v[30:31]
	v_pk_mul_f32 v[36:37], v[48:49], v[46:47]
	v_pk_mul_f32 v[38:39], v[50:51], v[114:115]
	v_mad_i64_i32 v[34:35], s[6:7], v54, s41, v[68:69]
	v_pk_mul_f32 v[28:29], v[36:37], v[28:29]
	v_pk_mul_f32 v[30:31], v[38:39], v[30:31]
	v_lshl_add_u64 v[34:35], v[34:35], 0, v[64:65]
	v_cvt_pk_bf16_f32 v28, v28, v29
	v_cvt_pk_bf16_f32 v29, v30, v31
	global_store_dwordx2 v[34:35], v[28:29], off
	s_nop 0
	v_pk_mul_f32 v[24:25], v[24:25], v[44:45] op_sel_hi:[1,0]
	v_pk_mul_f32 v[26:27], v[26:27], v[44:45] op_sel_hi:[1,0]
	s_add_i32 s25, s25, s27
	s_add_u32 s12, s12, s14
	s_addc_u32 s13, s13, s15
	s_add_u32 s16, s16, s18
	s_addc_u32 s17, s17, s19
	s_cmpk_gt_i32 s1, 0x3ff
	v_lshlrev_b32_e32 v38, 16, v116
	v_and_b32_e32 v39, 0xffff0000, v116
	v_lshlrev_b32_e32 v116, 16, v117
	v_and_b32_e32 v117, 0xffff0000, v117
	v_mul_f32_e32 v33, 0xbfb8aa3b, v38
	v_mul_f32_e32 v40, 0xbfb8aa3b, v39
	v_mul_f32_e32 v41, 0xbfb8aa3b, v116
	v_mul_f32_e32 v45, 0xbfb8aa3b, v117
	v_exp_f32_e32 v33, v33
	v_exp_f32_e32 v40, v40
	v_exp_f32_e32 v41, v41
	v_exp_f32_e32 v45, v45
	v_add_f32_e32 v33, 1.0, v33
	v_add_f32_e32 v46, 1.0, v40
	v_add_f32_e32 v47, 1.0, v41
	v_add_f32_e32 v45, 1.0, v45
	v_rcp_f32_e32 v40, v33
	v_rcp_f32_e32 v41, v46
	v_rcp_f32_e32 v46, v47
	v_rcp_f32_e32 v47, v45
	v_pk_mul_f32 v[24:25], v[134:135], v[24:25]
	v_pk_mul_f32 v[26:27], v[136:137], v[26:27]
	v_pk_mul_f32 v[28:29], v[40:41], v[38:39]
	v_pk_mul_f32 v[30:31], v[46:47], v[116:117]
	v_pk_mul_f32 v[24:25], v[24:25], v[28:29]
	v_pk_mul_f32 v[26:27], v[26:27], v[30:31]
	v_cvt_pk_bf16_f32 v24, v24, v25
	v_cvt_pk_bf16_f32 v25, v26, v27
	global_store_dwordx2 v[34:35], v[24:25], off offset:32
	s_nop 0
	v_pk_mul_f32 v[20:21], v[20:21], v[44:45] op_sel_hi:[1,0]
	v_pk_mul_f32 v[22:23], v[22:23], v[44:45] op_sel_hi:[1,0]
	v_pk_mul_f32 v[16:17], v[16:17], v[44:45] op_sel_hi:[1,0]
	v_pk_mul_f32 v[18:19], v[18:19], v[44:45] op_sel_hi:[1,0]
	v_lshlrev_b32_e32 v30, 16, v118
	v_and_b32_e32 v31, 0xffff0000, v118
	v_lshlrev_b32_e32 v118, 16, v119
	v_and_b32_e32 v119, 0xffff0000, v119
	v_mul_f32_e32 v33, 0xbfb8aa3b, v30
	v_mul_f32_e32 v36, 0xbfb8aa3b, v31
	v_mul_f32_e32 v37, 0xbfb8aa3b, v118
	v_mul_f32_e32 v38, 0xbfb8aa3b, v119
	v_exp_f32_e32 v33, v33
	v_exp_f32_e32 v36, v36
	v_exp_f32_e32 v37, v37
	v_exp_f32_e32 v38, v38
	v_add_f32_e32 v33, 1.0, v33
	v_add_f32_e32 v39, 1.0, v36
	v_add_f32_e32 v40, 1.0, v37
; __device__ __forceinline__ float bf_lo(unsigned u) { return __uint_as_float(u << 16); }
; __device__ __forceinline__ float bf_hi(unsigned u) { return __uint_as_float(u & 0xffff0000u); }
; __device__ __forceinline__ float siluf_(float x) { return x * __builtin_amdgcn_rcpf(1.f + __expf(-x)); }
; __device__ void phaseG3_task(const Params& p, int task, char* lds, bf16_t* ydst, int ystride) {
;     ...
; #pragma unroll
;     for (int tt = 0; tt < 4; tt++) {
;         const int t = tt * 16 + r;
;         const float tot = red[t] + red[64 + t] + red[128 + t] + red[192 + t];
;         const float rstd = rsqrtf(tot * (1.f / 256.f) + 1e-6f);
; #pragma unroll
;         for (int et = 0; et < 4; et++) {
;             const int e = (wave * 4 + et) * 16 + 4 * q;
;             bf16_t* rp = Z + (size_t)(tok0 + t) * ZC + ZR_G + h * 256 + e;
;             const u32x2 rv = *(const u32x2*)rp;
;             const f32x4 gn = *(const f32x4*)(p.gla_norm_g + e);
;             const float r0 = bf_lo(rv.x), r1 = bf_hi(rv.x), r2 = bf_lo(rv.y), r3 = bf_hi(rv.y);
;             const f32x4 ov = o[et][tt];
;             *(u32x2*)(ydst + (size_t)(tok0 + t) * ystride + h * 256 + e) = (u32x2){pack2(ov[0] * rstd * gn[0] * siluf_(r0), ov[1] * rstd * gn[1] * siluf_(r1)),
;                                   pack2(ov[2] * rstd * gn[2] * siluf_(r2), ov[3] * rstd * gn[3] * siluf_(r3))};
;         }
;     }
	v_add_f32_e32 v41, 1.0, v38
	v_rcp_f32_e32 v36, v33
	v_rcp_f32_e32 v37, v39
	v_rcp_f32_e32 v38, v40
	v_rcp_f32_e32 v39, v41
	v_pk_mul_f32 v[20:21], v[138:139], v[20:21]
	v_pk_mul_f32 v[22:23], v[140:141], v[22:23]
	v_pk_mul_f32 v[24:25], v[36:37], v[30:31]
	v_pk_mul_f32 v[26:27], v[38:39], v[118:119]
	v_pk_mul_f32 v[20:21], v[20:21], v[24:25]
	v_pk_mul_f32 v[22:23], v[22:23], v[26:27]
	v_cvt_pk_bf16_f32 v20, v20, v21
	v_cvt_pk_bf16_f32 v21, v22, v23
	global_store_dwordx2 v[34:35], v[20:21], off offset:64
	s_nop 0
	v_or_b32_e32 v33, s0, v78
	v_mad_i64_i32 v[26:27], s[6:7], v33, s41, v[66:67]
	v_lshl_add_u64 v[26:27], v[26:27], 0, s[10:11]
	v_lshl_add_u64 v[26:27], v[26:27], 0, v[64:65]
	v_add_co_u32_e32 v28, vcc, s9, v26
	v_lshlrev_b32_e32 v30, 16, v120
	v_and_b32_e32 v31, 0xffff0000, v120
	v_lshlrev_b32_e32 v120, 16, v121
	v_and_b32_e32 v121, 0xffff0000, v121
	v_mul_f32_e32 v36, 0xbfb8aa3b, v30
	v_mul_f32_e32 v37, 0xbfb8aa3b, v31
	v_mul_f32_e32 v38, 0xbfb8aa3b, v120
	v_mul_f32_e32 v39, 0xbfb8aa3b, v121
	v_exp_f32_e32 v36, v36
	v_exp_f32_e32 v37, v37
	v_exp_f32_e32 v38, v38
	v_exp_f32_e32 v39, v39
	v_add_f32_e32 v36, 1.0, v36
	v_add_f32_e32 v37, 1.0, v37
	v_add_f32_e32 v38, 1.0, v38
	v_add_f32_e32 v39, 1.0, v39
	v_rcp_f32_e32 v36, v36
	v_rcp_f32_e32 v37, v37
	v_rcp_f32_e32 v38, v38
	v_rcp_f32_e32 v39, v39
	v_pk_mul_f32 v[16:17], v[16:17], v[142:143]
	v_pk_mul_f32 v[18:19], v[18:19], v[144:145]
	v_pk_mul_f32 v[20:21], v[36:37], v[30:31]
	v_pk_mul_f32 v[22:23], v[38:39], v[120:121]
	v_pk_mul_f32 v[16:17], v[16:17], v[20:21]
	v_pk_mul_f32 v[18:19], v[18:19], v[22:23]
	v_cvt_pk_bf16_f32 v16, v16, v17
	v_cvt_pk_bf16_f32 v17, v18, v19
	v_addc_co_u32_e32 v29, vcc, 0, v27, vcc
	global_store_dwordx2 v[34:35], v[16:17], off offset:96
	v_mul_f32_e32 v16, 0x4b800000, v32
	v_cmp_gt_f32_e32 vcc, s44, v32
	v_lshl_add_u64 v[24:25], v[26:27], 0, s[22:23]
	v_lshlrev_b32_e32 v28, 16, v122
	v_cndmask_b32_e32 v16, v32, v16, vcc
	v_rsq_f32_e32 v26, v16
	v_and_b32_e32 v29, 0xffff0000, v122
	v_lshlrev_b32_e32 v122, 16, v123
	v_and_b32_e32 v123, 0xffff0000, v123
	v_mul_f32_e32 v27, 0x45800000, v26
	v_cndmask_b32_e32 v26, v26, v27, vcc
	v_pk_mul_f32 v[12:13], v[12:13], v[26:27] op_sel_hi:[1,0]
	v_pk_mul_f32 v[14:15], v[14:15], v[26:27] op_sel_hi:[1,0]
	v_mul_f32_e32 v27, 0xbfb8aa3b, v28
	v_mul_f32_e32 v30, 0xbfb8aa3b, v29
	v_mul_f32_e32 v31, 0xbfb8aa3b, v122
	v_mul_f32_e32 v32, 0xbfb8aa3b, v123
	v_exp_f32_e32 v27, v27
	v_exp_f32_e32 v30, v30
	v_exp_f32_e32 v31, v31
	v_exp_f32_e32 v32, v32
	v_mad_i64_i32 v[16:17], s[6:7], v33, s41, v[68:69]
	v_add_f32_e32 v27, 1.0, v27
	v_add_f32_e32 v33, 1.0, v30
	v_add_f32_e32 v34, 1.0, v31
	v_add_f32_e32 v35, 1.0, v32
	v_rcp_f32_e32 v30, v27
	v_rcp_f32_e32 v31, v33
	v_rcp_f32_e32 v32, v34
	v_rcp_f32_e32 v33, v35
	v_pk_mul_f32 v[12:13], v[130:131], v[12:13]
	v_pk_mul_f32 v[14:15], v[132:133], v[14:15]
	v_pk_mul_f32 v[18:19], v[30:31], v[28:29]
	v_pk_mul_f32 v[20:21], v[32:33], v[122:123]
	v_pk_mul_f32 v[12:13], v[18:19], v[12:13]
	v_pk_mul_f32 v[14:15], v[20:21], v[14:15]
	v_lshl_add_u64 v[16:17], v[16:17], 0, v[64:65]
	v_cvt_pk_bf16_f32 v12, v12, v13
	v_cvt_pk_bf16_f32 v13, v14, v15
	global_store_dwordx2 v[16:17], v[12:13], off
	s_nop 0
	v_pk_mul_f32 v[8:9], v[8:9], v[26:27] op_sel_hi:[1,0]
	v_pk_mul_f32 v[10:11], v[10:11], v[26:27] op_sel_hi:[1,0]
	v_lshlrev_b32_e32 v20, 16, v124
	v_and_b32_e32 v21, 0xffff0000, v124
	v_lshlrev_b32_e32 v124, 16, v125
	v_and_b32_e32 v125, 0xffff0000, v125
	v_mul_f32_e32 v22, 0xbfb8aa3b, v20
	v_mul_f32_e32 v23, 0xbfb8aa3b, v21
	v_mul_f32_e32 v27, 0xbfb8aa3b, v124
	v_mul_f32_e32 v28, 0xbfb8aa3b, v125
	v_exp_f32_e32 v22, v22
	v_exp_f32_e32 v23, v23
	v_exp_f32_e32 v27, v27
	v_exp_f32_e32 v28, v28
	v_add_f32_e32 v22, 1.0, v22
	v_add_f32_e32 v23, 1.0, v23
	v_add_f32_e32 v27, 1.0, v27
	v_add_f32_e32 v29, 1.0, v28
	v_rcp_f32_e32 v22, v22
	v_rcp_f32_e32 v23, v23
	v_rcp_f32_e32 v28, v27
	v_rcp_f32_e32 v29, v29
	v_pk_mul_f32 v[8:9], v[134:135], v[8:9]
	v_pk_mul_f32 v[10:11], v[136:137], v[10:11]
	v_pk_mul_f32 v[12:13], v[22:23], v[20:21]
	v_pk_mul_f32 v[14:15], v[28:29], v[124:125]
	v_pk_mul_f32 v[8:9], v[8:9], v[12:13]
	v_pk_mul_f32 v[10:11], v[10:11], v[14:15]
	v_cvt_pk_bf16_f32 v8, v8, v9
	v_cvt_pk_bf16_f32 v9, v10, v11
	global_store_dwordx2 v[16:17], v[8:9], off offset:32
	s_nop 0
	v_pk_mul_f32 v[4:5], v[4:5], v[26:27] op_sel_hi:[1,0]
	v_pk_mul_f32 v[6:7], v[6:7], v[26:27] op_sel_hi:[1,0]
	v_pk_mul_f32 v[0:1], v[0:1], v[26:27] op_sel_hi:[1,0]
	v_pk_mul_f32 v[2:3], v[2:3], v[26:27] op_sel_hi:[1,0]
	v_lshlrev_b32_e32 v14, 16, v126
	v_and_b32_e32 v15, 0xffff0000, v126
	v_lshlrev_b32_e32 v126, 16, v127
	v_and_b32_e32 v127, 0xffff0000, v127
	v_mul_f32_e32 v18, 0xbfb8aa3b, v14
	v_mul_f32_e32 v19, 0xbfb8aa3b, v15
	v_mul_f32_e32 v20, 0xbfb8aa3b, v126
	v_mul_f32_e32 v21, 0xbfb8aa3b, v127
	v_exp_f32_e32 v18, v18
	v_exp_f32_e32 v19, v19
	v_exp_f32_e32 v20, v20
	v_exp_f32_e32 v21, v21
	v_add_f32_e32 v18, 1.0, v18
	v_add_f32_e32 v19, 1.0, v19
	v_add_f32_e32 v20, 1.0, v20
	v_add_f32_e32 v21, 1.0, v21
	v_rcp_f32_e32 v18, v18
	v_rcp_f32_e32 v19, v19
	v_rcp_f32_e32 v20, v20
	v_rcp_f32_e32 v21, v21
	v_pk_mul_f32 v[4:5], v[138:139], v[4:5]
	v_pk_mul_f32 v[6:7], v[140:141], v[6:7]
	v_pk_mul_f32 v[8:9], v[18:19], v[14:15]
	v_pk_mul_f32 v[10:11], v[20:21], v[126:127]
	v_pk_mul_f32 v[4:5], v[4:5], v[8:9]
	v_pk_mul_f32 v[6:7], v[6:7], v[10:11]
	v_cvt_pk_bf16_f32 v4, v4, v5
	v_cvt_pk_bf16_f32 v5, v6, v7
	global_store_dwordx2 v[16:17], v[4:5], off offset:64
	s_nop 0
	v_lshlrev_b32_e32 v10, 16, v128
	v_and_b32_e32 v11, 0xffff0000, v128
	v_lshlrev_b32_e32 v128, 16, v129
	v_and_b32_e32 v129, 0xffff0000, v129
	v_mul_f32_e32 v12, 0xbfb8aa3b, v10
	v_mul_f32_e32 v13, 0xbfb8aa3b, v11
	v_mul_f32_e32 v14, 0xbfb8aa3b, v128
	v_mul_f32_e32 v15, 0xbfb8aa3b, v129
	v_exp_f32_e32 v12, v12
	v_exp_f32_e32 v13, v13
	v_exp_f32_e32 v14, v14
	v_exp_f32_e32 v15, v15
	v_add_f32_e32 v12, 1.0, v12
	v_add_f32_e32 v13, 1.0, v13
	v_add_f32_e32 v14, 1.0, v14
	v_add_f32_e32 v15, 1.0, v15
	v_rcp_f32_e32 v12, v12
	v_rcp_f32_e32 v13, v13
	v_rcp_f32_e32 v14, v14
	v_rcp_f32_e32 v15, v15
	v_pk_mul_f32 v[0:1], v[0:1], v[142:143]
	v_pk_mul_f32 v[2:3], v[2:3], v[144:145]
	v_pk_mul_f32 v[4:5], v[12:13], v[10:11]
	v_pk_mul_f32 v[6:7], v[14:15], v[128:129]
	v_pk_mul_f32 v[0:1], v[0:1], v[4:5]
	v_pk_mul_f32 v[2:3], v[2:3], v[6:7]
	v_cvt_pk_bf16_f32 v0, v0, v1
	v_cvt_pk_bf16_f32 v1, v2, v3
	global_store_dwordx2 v[16:17], v[0:1], off offset:96
	s_barrier
	s_cbranch_scc1 .LBB0_649
